# GUP loop: skip the first two counted vmcnt waits in a tile's first K-iteration (already drained by the epilogue) to avoid stalling on in-order store retirement
# baseline (speedup 1.0000x reference)
.LBB0_243:
	s_add_u32 s70, s42, 0xfffc0080
	s_addc_u32 s71, s43, -1
	s_add_i32 s72, 0, 0x10000
	s_cmp_eq_u32 s95, 12
	s_cselect_b32 vcc_hi, s2, s71
	s_cselect_b32 vcc_lo, s6, s70
	v_add_u32_e32 v0, s72, v181
	s_cselect_b32 s93, s41, s89
	s_cselect_b32 s92, s48, s77
	s_add_i32 s73, 0, 0x14000
	ds_read_b128 v[14:17], v0
	ds_read_b128 v[22:25], v0 offset:1024
	ds_read_b128 v[26:29], v0 offset:2048
	ds_read_b128 v[74:77], v0 offset:3072
	v_add_u32_e32 v0, s73, v181
	ds_read_b128 v[78:81], v0
	ds_read_b128 v[82:85], v0 offset:1024
	ds_read_b128 v[154:157], v0 offset:2048
	ds_read_b128 v[158:161], v0 offset:3072
	v_lshl_add_u64 v[174:175], s[42:43], 0, v[170:171]
	s_add_i32 m0, s81, 0xc000
	ds_read_b128 v[182:185], v189
	ds_read_b128 v[190:193], v189 offset:1024
	ds_read_b128 v[194:197], v189 offset:2048
	ds_read_b128 v[198:201], v189 offset:3072
	ds_read_b128 v[202:205], v189 offset:4096
	ds_read_b128 v[210:213], v189 offset:5120
	ds_read_b128 v[214:217], v189 offset:6144
	ds_read_b128 v[218:221], v189 offset:7168
	global_load_lds_dwordx4 v[174:175], off
	v_lshl_add_u64 v[174:175], s[42:43], 0, v[172:173]
	s_add_i32 m0, s81, 0xe000
	s_nop 0
	global_load_lds_dwordx4 v[174:175], off
	s_cmp_eq_u32 s95, -2
	s_cbranch_scc1 .Lgup_skip_w0
	s_waitcnt vmcnt(8)
.Lgup_skip_w0:
	s_waitcnt lgkmcnt(0)
	s_barrier
	s_setprio 1
	s_waitcnt lgkmcnt(0)
	v_mfma_f32_16x16x32_bf16 v[150:153], v[14:17], v[182:185], v[150:153]
	v_mfma_f32_16x16x32_bf16 v[58:61], v[26:29], v[182:185], v[58:61]
	v_mfma_f32_16x16x32_bf16 v[126:129], v[14:17], v[194:197], v[126:129]
	v_mfma_f32_16x16x32_bf16 v[122:125], v[26:29], v[194:197], v[122:125]
	v_mfma_f32_16x16x32_bf16 v[118:121], v[14:17], v[202:205], v[118:121]
	v_mfma_f32_16x16x32_bf16 v[114:117], v[26:29], v[202:205], v[114:117]
	v_mfma_f32_16x16x32_bf16 v[134:137], v[14:17], v[214:217], v[134:137]
	v_mfma_f32_16x16x32_bf16 v[130:133], v[26:29], v[214:217], v[130:133]
	v_mfma_f32_16x16x32_bf16 v[142:145], v[78:81], v[182:185], v[142:145]
	v_mfma_f32_16x16x32_bf16 v[138:141], v[154:157], v[182:185], v[138:141]
	v_mfma_f32_16x16x32_bf16 v[110:113], v[78:81], v[194:197], v[110:113]
	v_mfma_f32_16x16x32_bf16 v[106:109], v[154:157], v[194:197], v[106:109]
	v_mfma_f32_16x16x32_bf16 v[102:105], v[78:81], v[202:205], v[102:105]
	v_mfma_f32_16x16x32_bf16 v[98:101], v[154:157], v[202:205], v[98:101]
	v_mfma_f32_16x16x32_bf16 v[94:97], v[78:81], v[214:217], v[94:97]
	v_mfma_f32_16x16x32_bf16 v[90:93], v[154:157], v[214:217], v[90:93]
	v_mfma_f32_16x16x32_bf16 v[150:153], v[22:25], v[190:193], v[150:153]
	v_mfma_f32_16x16x32_bf16 v[58:61], v[74:77], v[190:193], v[58:61]
	v_mfma_f32_16x16x32_bf16 v[126:129], v[22:25], v[198:201], v[126:129]
	v_mfma_f32_16x16x32_bf16 v[122:125], v[74:77], v[198:201], v[122:125]
	v_mfma_f32_16x16x32_bf16 v[118:121], v[22:25], v[210:213], v[118:121]
	v_mfma_f32_16x16x32_bf16 v[114:117], v[74:77], v[210:213], v[114:117]
	v_mfma_f32_16x16x32_bf16 v[134:137], v[22:25], v[218:221], v[134:137]
	v_mfma_f32_16x16x32_bf16 v[130:133], v[74:77], v[218:221], v[130:133]
	v_mfma_f32_16x16x32_bf16 v[142:145], v[82:85], v[190:193], v[142:145]
	v_mfma_f32_16x16x32_bf16 v[138:141], v[158:161], v[190:193], v[138:141]
	v_mfma_f32_16x16x32_bf16 v[110:113], v[82:85], v[198:201], v[110:113]
	v_mfma_f32_16x16x32_bf16 v[106:109], v[158:161], v[198:201], v[106:109]
	v_mfma_f32_16x16x32_bf16 v[102:105], v[82:85], v[210:213], v[102:105]
	v_mfma_f32_16x16x32_bf16 v[98:101], v[158:161], v[210:213], v[98:101]
	v_mfma_f32_16x16x32_bf16 v[94:97], v[82:85], v[218:221], v[94:97]
	v_mfma_f32_16x16x32_bf16 v[90:93], v[158:161], v[218:221], v[90:93]
	s_setprio 0
	s_barrier
	s_add_i32 s70, s72, s29
	v_lshl_add_u64 v[174:175], s[92:93], 0, v[164:165]
	s_mov_b32 m0, s70
	ds_read_b128 v[182:185], v189 offset:16384
	ds_read_b128 v[190:193], v189 offset:17408
	ds_read_b128 v[194:197], v189 offset:18432
	ds_read_b128 v[198:201], v189 offset:19456
	ds_read_b128 v[202:205], v189 offset:20480
	ds_read_b128 v[210:213], v189 offset:21504
	ds_read_b128 v[214:217], v189 offset:22528
	ds_read_b128 v[218:221], v189 offset:23552
	global_load_lds_dwordx4 v[174:175], off
	s_add_i32 m0, s70, 0x2000
	s_add_u32 s70, s92, 0x40000
	v_lshl_add_u64 v[186:187], s[92:93], 0, v[168:169]
	s_addc_u32 s71, s93, 0
	s_add_i32 s72, s73, s29
	global_load_lds_dwordx4 v[186:187], off
	v_lshl_add_u64 v[206:207], s[70:71], 0, v[164:165]
	s_mov_b32 m0, s72
	v_lshl_add_u64 v[226:227], vcc, 0, v[166:167]
	global_load_lds_dwordx4 v[206:207], off
	v_lshl_add_u64 v[206:207], s[70:71], 0, v[168:169]
	s_add_i32 m0, s72, 0x2000
	s_nop 0
	global_load_lds_dwordx4 v[206:207], off
	v_lshl_add_u64 v[206:207], vcc, 0, v[162:163]
	s_mov_b32 m0, s81
	s_nop 0
	global_load_lds_dwordx4 v[206:207], off
	s_mov_b32 m0, s83
	s_nop 0
	global_load_lds_dwordx4 v[226:227], off
	s_cmp_lg_u32 s95, -2
	s_cbranch_scc1 .Lgup_do_w1
	s_cmp_lg_u32 s23, 1
	s_cbranch_scc1 .Lgup_skip_w1
.Lgup_do_w1:
	s_waitcnt vmcnt(8)
.Lgup_skip_w1:
	s_waitcnt lgkmcnt(0)
	s_barrier
	s_setprio 1
	s_waitcnt lgkmcnt(0)
	v_mfma_f32_16x16x32_bf16 v[70:73], v[14:17], v[182:185], v[70:73]
	v_mfma_f32_16x16x32_bf16 v[66:69], v[26:29], v[182:185], v[66:69]
	v_mfma_f32_16x16x32_bf16 v[62:65], v[14:17], v[194:197], v[62:65]
	v_mfma_f32_16x16x32_bf16 v[54:57], v[26:29], v[194:197], v[54:57]
	v_mfma_f32_16x16x32_bf16 v[42:45], v[14:17], v[202:205], v[42:45]
	v_mfma_f32_16x16x32_bf16 v[38:41], v[26:29], v[202:205], v[38:41]
	v_mfma_f32_16x16x32_bf16 v[14:17], v[14:17], v[214:217], v[86:89]
	v_mfma_f32_16x16x32_bf16 v[46:49], v[154:157], v[182:185], v[46:49]
	v_mfma_f32_16x16x32_bf16 v[34:37], v[78:81], v[194:197], v[34:37]
	v_mfma_f32_16x16x32_bf16 v[30:33], v[154:157], v[194:197], v[30:33]
	v_mfma_f32_16x16x32_bf16 v[18:21], v[78:81], v[202:205], v[18:21]
	v_mfma_f32_16x16x32_bf16 v[10:13], v[154:157], v[202:205], v[10:13]
	v_mfma_f32_16x16x32_bf16 v[6:9], v[78:81], v[214:217], v[6:9]
	v_mfma_f32_16x16x32_bf16 v[2:5], v[154:157], v[214:217], v[2:5]
	v_mfma_f32_16x16x32_bf16 v[70:73], v[22:25], v[190:193], v[70:73]
	v_mfma_f32_16x16x32_bf16 v[66:69], v[74:77], v[190:193], v[66:69]
	v_mfma_f32_16x16x32_bf16 v[62:65], v[22:25], v[198:201], v[62:65]
	v_mfma_f32_16x16x32_bf16 v[54:57], v[74:77], v[198:201], v[54:57]
	v_mfma_f32_16x16x32_bf16 v[42:45], v[22:25], v[210:213], v[42:45]
	v_mfma_f32_16x16x32_bf16 v[38:41], v[74:77], v[210:213], v[38:41]
	v_mfma_f32_16x16x32_bf16 v[14:17], v[22:25], v[218:221], v[14:17]
	v_mfma_f32_16x16x32_bf16 v[22:25], v[26:29], v[214:217], v[146:149]
	v_mfma_f32_16x16x32_bf16 v[26:29], v[78:81], v[182:185], v[50:53]
	v_mfma_f32_16x16x32_bf16 v[46:49], v[158:161], v[190:193], v[46:49]
	v_mfma_f32_16x16x32_bf16 v[34:37], v[82:85], v[198:201], v[34:37]
	v_mfma_f32_16x16x32_bf16 v[30:33], v[158:161], v[198:201], v[30:33]
	v_mfma_f32_16x16x32_bf16 v[18:21], v[82:85], v[210:213], v[18:21]
	v_mfma_f32_16x16x32_bf16 v[10:13], v[158:161], v[210:213], v[10:13]
	v_mfma_f32_16x16x32_bf16 v[6:9], v[82:85], v[218:221], v[6:9]
	v_mfma_f32_16x16x32_bf16 v[2:5], v[158:161], v[218:221], v[2:5]
	v_mfma_f32_16x16x32_bf16 v[22:25], v[74:77], v[218:221], v[22:25]
	v_mfma_f32_16x16x32_bf16 v[26:29], v[82:85], v[190:193], v[26:29]
	s_setprio 0
	s_barrier
	s_add_i32 s72, 0, 0x18000
	v_add_u32_e32 v0, s72, v181
	s_add_i32 s73, 0, 0x1c000
	ds_read_b128 v[50:53], v0
	ds_read_b128 v[74:77], v0 offset:1024
	ds_read_b128 v[78:81], v0 offset:2048
	ds_read_b128 v[82:85], v0 offset:3072
	v_add_u32_e32 v0, s73, v181
	ds_read_b128 v[154:157], v0
	ds_read_b128 v[158:161], v0 offset:1024
	ds_read_b128 v[182:185], v0 offset:2048
	ds_read_b128 v[190:193], v0 offset:3072
	s_add_u32 s70, vcc_lo, 0x40000
	s_addc_u32 s71, vcc_hi, 0
	s_mov_b32 m0, s16
	v_lshl_add_u64 v[222:223], s[70:71], 0, v[162:163]
	ds_read_b128 v[86:89], v189 offset:32768
	ds_read_b128 v[146:149], v189 offset:33792
	ds_read_b128 v[194:197], v189 offset:34816
	ds_read_b128 v[198:201], v189 offset:35840
	ds_read_b128 v[202:205], v189 offset:36864
	ds_read_b128 v[210:213], v189 offset:37888
	ds_read_b128 v[214:217], v189 offset:38912
	ds_read_b128 v[218:221], v189 offset:39936
	global_load_lds_dwordx4 v[222:223], off
	v_lshl_add_u64 v[222:223], s[70:71], 0, v[166:167]
	s_mov_b32 m0, s17
	s_nop 0
	global_load_lds_dwordx4 v[222:223], off
	s_waitcnt vmcnt(8)
	s_waitcnt lgkmcnt(0)
	s_barrier
	s_setprio 1
	s_waitcnt lgkmcnt(0)
	v_mfma_f32_16x16x32_bf16 v[150:153], v[50:53], v[86:89], v[150:153]
	v_mfma_f32_16x16x32_bf16 v[58:61], v[78:81], v[86:89], v[58:61]
	v_mfma_f32_16x16x32_bf16 v[142:145], v[154:157], v[86:89], v[142:145]
	v_mfma_f32_16x16x32_bf16 v[86:89], v[182:185], v[86:89], v[138:141]
	v_mfma_f32_16x16x32_bf16 v[138:141], v[190:193], v[146:149], v[86:89]
	v_mfma_f32_16x16x32_bf16 v[86:89], v[154:157], v[194:197], v[110:113]
	v_mfma_f32_16x16x32_bf16 v[110:113], v[158:161], v[198:201], v[86:89]
	v_mfma_f32_16x16x32_bf16 v[86:89], v[182:185], v[194:197], v[106:109]
	v_mfma_f32_16x16x32_bf16 v[106:109], v[190:193], v[198:201], v[86:89]
	v_mfma_f32_16x16x32_bf16 v[86:89], v[154:157], v[202:205], v[102:105]
	v_mfma_f32_16x16x32_bf16 v[102:105], v[158:161], v[210:213], v[86:89]
	v_mfma_f32_16x16x32_bf16 v[86:89], v[182:185], v[202:205], v[98:101]
	v_mfma_f32_16x16x32_bf16 v[98:101], v[190:193], v[210:213], v[86:89]
	v_mfma_f32_16x16x32_bf16 v[86:89], v[154:157], v[214:217], v[94:97]
	v_mfma_f32_16x16x32_bf16 v[126:129], v[50:53], v[194:197], v[126:129]
	v_mfma_f32_16x16x32_bf16 v[122:125], v[78:81], v[194:197], v[122:125]
	v_mfma_f32_16x16x32_bf16 v[118:121], v[50:53], v[202:205], v[118:121]
	v_mfma_f32_16x16x32_bf16 v[114:117], v[78:81], v[202:205], v[114:117]
	v_mfma_f32_16x16x32_bf16 v[134:137], v[50:53], v[214:217], v[134:137]
	v_mfma_f32_16x16x32_bf16 v[130:133], v[78:81], v[214:217], v[130:133]
	v_mfma_f32_16x16x32_bf16 v[94:97], v[158:161], v[218:221], v[86:89]
	v_mfma_f32_16x16x32_bf16 v[86:89], v[182:185], v[214:217], v[90:93]
	v_mfma_f32_16x16x32_bf16 v[150:153], v[74:77], v[146:149], v[150:153]
	v_mfma_f32_16x16x32_bf16 v[58:61], v[82:85], v[146:149], v[58:61]
	v_mfma_f32_16x16x32_bf16 v[126:129], v[74:77], v[198:201], v[126:129]
	v_mfma_f32_16x16x32_bf16 v[122:125], v[82:85], v[198:201], v[122:125]
	v_mfma_f32_16x16x32_bf16 v[118:121], v[74:77], v[210:213], v[118:121]
	v_mfma_f32_16x16x32_bf16 v[114:117], v[82:85], v[210:213], v[114:117]
	v_mfma_f32_16x16x32_bf16 v[134:137], v[74:77], v[218:221], v[134:137]
	v_mfma_f32_16x16x32_bf16 v[130:133], v[82:85], v[218:221], v[130:133]
	v_mfma_f32_16x16x32_bf16 v[142:145], v[158:161], v[146:149], v[142:145]
	v_mfma_f32_16x16x32_bf16 v[90:93], v[190:193], v[218:221], v[86:89]
	s_setprio 0
	s_barrier
	s_add_i32 s70, s72, s29
	v_lshl_add_u64 v[86:87], v[174:175], 0, s[34:35]
	s_mov_b32 m0, s70
	ds_read_b128 v[194:197], v189 offset:49152
	ds_read_b128 v[198:201], v189 offset:50176
	ds_read_b128 v[202:205], v189 offset:51200
	ds_read_b128 v[210:213], v189 offset:52224
	ds_read_b128 v[214:217], v189 offset:53248
	ds_read_b128 v[218:221], v189 offset:54272
	ds_read_b128 v[222:225], v189 offset:55296
	ds_read_b128 v[242:245], v189 offset:56320
	global_load_lds_dwordx4 v[86:87], off
	s_add_i32 m0, s70, 0x2000
	s_add_u32 s70, s92, 0x40080
	v_lshl_add_u64 v[86:87], v[186:187], 0, s[34:35]
	s_addc_u32 s71, s93, 0
	s_add_i32 s72, s73, s29
	global_load_lds_dwordx4 v[86:87], off
	v_lshl_add_u64 v[86:87], s[70:71], 0, v[164:165]
	s_mov_b32 m0, s72
	s_nop 0
	global_load_lds_dwordx4 v[86:87], off
	v_lshl_add_u64 v[86:87], s[70:71], 0, v[168:169]
	s_add_i32 m0, s72, 0x2000
	s_nop 0
	global_load_lds_dwordx4 v[86:87], off
	v_lshl_add_u64 v[86:87], v[206:207], 0, s[34:35]
	s_mov_b32 m0, s19
	s_nop 0
	global_load_lds_dwordx4 v[86:87], off
	v_lshl_add_u64 v[86:87], v[226:227], 0, s[34:35]
	s_mov_b32 m0, s20
	s_nop 0
	global_load_lds_dwordx4 v[86:87], off
	s_waitcnt vmcnt(8)
	s_waitcnt lgkmcnt(0)
	s_barrier
	s_setprio 1
	s_waitcnt lgkmcnt(0)
	v_mfma_f32_16x16x32_bf16 v[14:17], v[50:53], v[222:225], v[14:17]
	v_mfma_f32_16x16x32_bf16 v[86:89], v[74:77], v[242:245], v[14:17]
	v_mfma_f32_16x16x32_bf16 v[14:17], v[78:81], v[222:225], v[22:25]
	v_mfma_f32_16x16x32_bf16 v[146:149], v[82:85], v[242:245], v[14:17]
	v_mfma_f32_16x16x32_bf16 v[14:17], v[154:157], v[194:197], v[26:29]
	v_mfma_f32_16x16x32_bf16 v[70:73], v[50:53], v[194:197], v[70:73]
	v_mfma_f32_16x16x32_bf16 v[62:65], v[50:53], v[202:205], v[62:65]
	v_mfma_f32_16x16x32_bf16 v[42:45], v[50:53], v[214:217], v[42:45]
	v_mfma_f32_16x16x32_bf16 v[50:53], v[158:161], v[198:201], v[14:17]
	v_mfma_f32_16x16x32_bf16 v[14:17], v[182:185], v[194:197], v[46:49]
	v_mfma_f32_16x16x32_bf16 v[46:49], v[190:193], v[198:201], v[14:17]
	v_mfma_f32_16x16x32_bf16 v[14:17], v[154:157], v[202:205], v[34:37]
	v_mfma_f32_16x16x32_bf16 v[34:37], v[158:161], v[210:213], v[14:17]
	v_mfma_f32_16x16x32_bf16 v[14:17], v[182:185], v[202:205], v[30:33]
	v_mfma_f32_16x16x32_bf16 v[66:69], v[78:81], v[194:197], v[66:69]
	v_mfma_f32_16x16x32_bf16 v[54:57], v[78:81], v[202:205], v[54:57]
	v_mfma_f32_16x16x32_bf16 v[38:41], v[78:81], v[214:217], v[38:41]
	v_mfma_f32_16x16x32_bf16 v[30:33], v[190:193], v[210:213], v[14:17]
	v_mfma_f32_16x16x32_bf16 v[14:17], v[154:157], v[214:217], v[18:21]
	v_mfma_f32_16x16x32_bf16 v[10:13], v[182:185], v[214:217], v[10:13]
	v_mfma_f32_16x16x32_bf16 v[6:9], v[154:157], v[222:225], v[6:9]
	v_mfma_f32_16x16x32_bf16 v[2:5], v[182:185], v[222:225], v[2:5]
	v_mfma_f32_16x16x32_bf16 v[70:73], v[74:77], v[198:201], v[70:73]
	v_mfma_f32_16x16x32_bf16 v[66:69], v[82:85], v[198:201], v[66:69]
	v_mfma_f32_16x16x32_bf16 v[62:65], v[74:77], v[210:213], v[62:65]
	v_mfma_f32_16x16x32_bf16 v[54:57], v[82:85], v[210:213], v[54:57]
	v_mfma_f32_16x16x32_bf16 v[42:45], v[74:77], v[218:221], v[42:45]
	v_mfma_f32_16x16x32_bf16 v[38:41], v[82:85], v[218:221], v[38:41]
	v_mfma_f32_16x16x32_bf16 v[18:21], v[158:161], v[218:221], v[14:17]
	v_mfma_f32_16x16x32_bf16 v[10:13], v[190:193], v[218:221], v[10:13]
	v_mfma_f32_16x16x32_bf16 v[6:9], v[158:161], v[242:245], v[6:9]
	v_mfma_f32_16x16x32_bf16 v[2:5], v[190:193], v[242:245], v[2:5]
	s_setprio 0
	s_barrier
	s_add_i32 s95, s95, 2
	s_add_u32 s42, s42, 0x100
	s_addc_u32 s43, s43, 0
	s_add_u32 s77, s77, 0x100
	s_addc_u32 s89, s89, 0
	s_cmp_gt_u32 s95, 13
	s_cbranch_scc0 .LBB0_243
	s_and_b64 vcc, exec, s[74:75]
	s_cbranch_vccz .LBB0_246
	s_barrier
